# hyena stage-1 and stage-3 loops: all 48 conv-tap loads of a trip issued together up front (was serialized per element), on top of previous version
# speedup vs baseline: 1.0311x; 1.0082x over previous
; DI void hyena_item(const Params& p, int l, int dpr, LAS unsigned char* lds) {
;     ...
;     for (int r = 0; r < 16; ++r) { const int t = tid + NTHR * r;
;         float v[4];
; #pragma unroll
;         for (int c = 0; c < 4; ++c) v[c] = conv3(bint + (size_t)(a + c) * S, t, w[c][0], w[c][1], w[c][2]) * 0.25f;
.LBB0_601:
	v_add_u32_e32 v22, s7, v12
	v_mov_b32_e32 v149, 0
	v_mov_b32_e32 v151, 0
	v_mov_b32_e32 v153, 0
	v_mov_b32_e32 v148, v22
	v_max_i32_e32 v150, 1, v148
	v_min_i32_e32 v152, 0x1ffe, v148
	v_lshlrev_b32_e32 v148, 2, v148
	v_lshlrev_b32_e32 v150, 2, v150
	v_lshlrev_b32_e32 v152, 2, v152
	v_lshl_add_u64 v[154:155], s[58:59], 0, v[148:149]
	global_load_dword v100, v[154:155], off
	v_lshl_add_u64 v[154:155], s[58:59], 0, v[150:151]
	global_load_dword v101, v[154:155], off offset:-4
	v_lshl_add_u64 v[154:155], s[58:59], 0, v[152:153]
	global_load_dword v102, v[154:155], off offset:4
	v_lshl_add_u64 v[154:155], s[62:63], 0, v[148:149]
	global_load_dword v103, v[154:155], off
	v_lshl_add_u64 v[154:155], s[62:63], 0, v[150:151]
	global_load_dword v104, v[154:155], off offset:-4
	v_lshl_add_u64 v[154:155], s[62:63], 0, v[152:153]
	global_load_dword v105, v[154:155], off offset:4
	v_lshl_add_u64 v[154:155], s[18:19], 0, v[148:149]
	global_load_dword v106, v[154:155], off
	v_lshl_add_u64 v[154:155], s[18:19], 0, v[150:151]
	global_load_dword v107, v[154:155], off offset:-4
	v_lshl_add_u64 v[154:155], s[18:19], 0, v[152:153]
	global_load_dword v108, v[154:155], off offset:4
	v_lshl_add_u64 v[154:155], s[16:17], 0, v[148:149]
	global_load_dword v109, v[154:155], off
	v_lshl_add_u64 v[154:155], s[16:17], 0, v[150:151]
	global_load_dword v110, v[154:155], off offset:-4
	v_lshl_add_u64 v[154:155], s[16:17], 0, v[152:153]
	global_load_dword v111, v[154:155], off offset:4
	v_add_u32_e32 v148, 0x200, v22
	v_max_i32_e32 v150, 1, v148
	v_min_i32_e32 v152, 0x1ffe, v148
	v_lshlrev_b32_e32 v148, 2, v148
	v_lshlrev_b32_e32 v150, 2, v150
	v_lshlrev_b32_e32 v152, 2, v152
	v_lshl_add_u64 v[154:155], s[58:59], 0, v[148:149]
	global_load_dword v112, v[154:155], off
	v_lshl_add_u64 v[154:155], s[58:59], 0, v[150:151]
	global_load_dword v113, v[154:155], off offset:-4
	v_lshl_add_u64 v[154:155], s[58:59], 0, v[152:153]
	global_load_dword v114, v[154:155], off offset:4
	v_lshl_add_u64 v[154:155], s[62:63], 0, v[148:149]
	global_load_dword v115, v[154:155], off
	v_lshl_add_u64 v[154:155], s[62:63], 0, v[150:151]
	global_load_dword v116, v[154:155], off offset:-4
	v_lshl_add_u64 v[154:155], s[62:63], 0, v[152:153]
	global_load_dword v117, v[154:155], off offset:4
	v_lshl_add_u64 v[154:155], s[18:19], 0, v[148:149]
	global_load_dword v118, v[154:155], off
	v_lshl_add_u64 v[154:155], s[18:19], 0, v[150:151]
	global_load_dword v119, v[154:155], off offset:-4
	v_lshl_add_u64 v[154:155], s[18:19], 0, v[152:153]
	global_load_dword v120, v[154:155], off offset:4
	v_lshl_add_u64 v[154:155], s[16:17], 0, v[148:149]
	global_load_dword v121, v[154:155], off
	v_lshl_add_u64 v[154:155], s[16:17], 0, v[150:151]
	global_load_dword v122, v[154:155], off offset:-4
	v_lshl_add_u64 v[154:155], s[16:17], 0, v[152:153]
	global_load_dword v123, v[154:155], off offset:4
	v_add_u32_e32 v148, 0x400, v22
	v_max_i32_e32 v150, 1, v148
	v_min_i32_e32 v152, 0x1ffe, v148
	v_lshlrev_b32_e32 v148, 2, v148
	v_lshlrev_b32_e32 v150, 2, v150
	v_lshlrev_b32_e32 v152, 2, v152
	v_lshl_add_u64 v[154:155], s[58:59], 0, v[148:149]
	global_load_dword v124, v[154:155], off
	v_lshl_add_u64 v[154:155], s[58:59], 0, v[150:151]
	global_load_dword v125, v[154:155], off offset:-4
	v_lshl_add_u64 v[154:155], s[58:59], 0, v[152:153]
	global_load_dword v126, v[154:155], off offset:4
	v_lshl_add_u64 v[154:155], s[62:63], 0, v[148:149]
	global_load_dword v127, v[154:155], off
	v_lshl_add_u64 v[154:155], s[62:63], 0, v[150:151]
	global_load_dword v128, v[154:155], off offset:-4
	v_lshl_add_u64 v[154:155], s[62:63], 0, v[152:153]
	global_load_dword v129, v[154:155], off offset:4
	v_lshl_add_u64 v[154:155], s[18:19], 0, v[148:149]
	global_load_dword v130, v[154:155], off
	v_lshl_add_u64 v[154:155], s[18:19], 0, v[150:151]
	global_load_dword v131, v[154:155], off offset:-4
	v_lshl_add_u64 v[154:155], s[18:19], 0, v[152:153]
	global_load_dword v132, v[154:155], off offset:4
	v_lshl_add_u64 v[154:155], s[16:17], 0, v[148:149]
	global_load_dword v133, v[154:155], off
	v_lshl_add_u64 v[154:155], s[16:17], 0, v[150:151]
	global_load_dword v134, v[154:155], off offset:-4
	v_lshl_add_u64 v[154:155], s[16:17], 0, v[152:153]
	global_load_dword v135, v[154:155], off offset:4
	v_add_u32_e32 v148, 0x600, v22
	v_max_i32_e32 v150, 1, v148
	v_min_i32_e32 v152, 0x1ffe, v148
	v_lshlrev_b32_e32 v148, 2, v148
	v_lshlrev_b32_e32 v150, 2, v150
	v_lshlrev_b32_e32 v152, 2, v152
	v_lshl_add_u64 v[154:155], s[58:59], 0, v[148:149]
	global_load_dword v136, v[154:155], off
	v_lshl_add_u64 v[154:155], s[58:59], 0, v[150:151]
	global_load_dword v137, v[154:155], off offset:-4
	v_lshl_add_u64 v[154:155], s[58:59], 0, v[152:153]
	global_load_dword v138, v[154:155], off offset:4
	v_lshl_add_u64 v[154:155], s[62:63], 0, v[148:149]
	global_load_dword v139, v[154:155], off
	v_lshl_add_u64 v[154:155], s[62:63], 0, v[150:151]
	global_load_dword v140, v[154:155], off offset:-4
	v_lshl_add_u64 v[154:155], s[62:63], 0, v[152:153]
	global_load_dword v141, v[154:155], off offset:4
	v_lshl_add_u64 v[154:155], s[18:19], 0, v[148:149]
	global_load_dword v142, v[154:155], off
	v_lshl_add_u64 v[154:155], s[18:19], 0, v[150:151]
	global_load_dword v143, v[154:155], off offset:-4
	v_lshl_add_u64 v[154:155], s[18:19], 0, v[152:153]
	global_load_dword v144, v[154:155], off offset:4
	v_lshl_add_u64 v[154:155], s[16:17], 0, v[148:149]
	global_load_dword v145, v[154:155], off
	v_lshl_add_u64 v[154:155], s[16:17], 0, v[150:151]
	global_load_dword v146, v[154:155], off offset:-4
	v_lshl_add_u64 v[154:155], s[16:17], 0, v[152:153]
	global_load_dword v147, v[154:155], off offset:4
	s_waitcnt vmcnt(0)
; DI void hyena_item(const Params& p, int l, int dpr, LAS unsigned char* lds) {
;     ...
;     for (int r = 0; r < 16; ++r) { const int t = tid + NTHR * r;
;         float v[4];
; #pragma unroll
;         for (int c = 0; c < 4; ++c) v[c] = conv3(bint + (size_t)(a + c) * S, t, w[c][0], w[c][1], w[c][2]) * 0.25f;
;         X0[XI(t)] = (hc){(_Float16)v[0], (_Float16)v[1]}; X1[XI(t)] = (hc){(_Float16)v[2], (_Float16)v[3]};
;         X0[XI(t + 8192)] = hzero; X1[XI(t + 8192)] = hzero; }
	v_ashrrev_i32_e32 v23, 31, v22
	v_max_i32_e32 v96, 1, v22
	v_min_i32_e32 v24, 0x1ffe, v22
	v_lshlrev_b64 v[26:27], 2, v[22:23]
	v_lshlrev_b64 v[30:31], 2, v[96:97]
	v_ashrrev_i32_e32 v25, 31, v24
	v_lshl_add_u64 v[28:29], s[58:59], 0, v[26:27]
	v_lshl_add_u64 v[32:33], s[58:59], 0, v[30:31]
	v_mov_b32_e32 v28, v100
	v_lshlrev_b64 v[24:25], 2, v[24:25]
	v_mov_b32_e32 v23, v101
	v_lshl_add_u64 v[32:33], s[58:59], 0, v[24:25]
	v_mov_b32_e32 v32, v102
	v_cmp_lt_i32_e32 vcc, 0, v22
	v_cmp_gt_i32_e64 s[40:41], s29, v22
	s_addk_i32 s7, 0x800
	s_cmpk_eq_i32 s7, 0x2000
	s_nop 0
	v_cndmask_b32_e32 v29, 0, v23, vcc
	v_pk_mul_f32 v[28:29], v[0:1], v[28:29]
	s_nop 0
	v_cndmask_b32_e64 v23, 0, v32, s[40:41]
	v_add_f32_e32 v28, v28, v29
	v_fmac_f32_e32 v28, v4, v23
	v_mul_f32_e32 v23, 0x3e800000, v28
	v_lshl_add_u64 v[28:29], s[62:63], 0, v[26:27]
	v_lshl_add_u64 v[32:33], s[62:63], 0, v[30:31]
	v_mov_b32_e32 v28, v103
	s_nop 0
	v_mov_b32_e32 v29, v104
	v_lshl_add_u64 v[32:33], s[62:63], 0, v[24:25]
	v_mov_b32_e32 v32, v105
	s_nop 0
	v_cndmask_b32_e32 v29, 0, v29, vcc
	v_pk_mul_f32 v[28:29], v[8:9], v[28:29]
	s_nop 0
	v_cndmask_b32_e64 v32, 0, v32, s[40:41]
	v_add_f32_e32 v28, v28, v29
	v_fmac_f32_e32 v28, v5, v32
	v_mul_f32_e32 v34, 0x3e800000, v28
	v_lshl_add_u64 v[28:29], s[18:19], 0, v[26:27]
	v_lshl_add_u64 v[32:33], s[18:19], 0, v[30:31]
	v_lshl_add_u64 v[26:27], s[16:17], 0, v[26:27]
	v_mov_b32_e32 v28, v106
	v_cvt_pk_f16_f32 v23, v23, v34
	v_mov_b32_e32 v26, v109
	s_nop 0
	v_mov_b32_e32 v29, v107
	v_lshl_add_u64 v[32:33], s[18:19], 0, v[24:25]
	v_mov_b32_e32 v32, v108
	v_lshl_add_u64 v[24:25], s[16:17], 0, v[24:25]
	v_mov_b32_e32 v24, v111
	s_nop 0
	v_cndmask_b32_e32 v29, 0, v29, vcc
	v_pk_mul_f32 v[28:29], v[2:3], v[28:29]
	s_nop 0
	v_cndmask_b32_e64 v32, 0, v32, s[40:41]
	v_add_f32_e32 v28, v28, v29
	v_fmac_f32_e32 v28, v6, v32
	v_mul_f32_e32 v32, 0x3e800000, v28
	v_lshl_add_u64 v[28:29], s[16:17], 0, v[30:31]
	v_mov_b32_e32 v27, v110
	s_nop 0
	v_cndmask_b32_e64 v28, 0, v24, s[40:41]
	s_nop 0
	v_cndmask_b32_e32 v27, 0, v27, vcc
	v_pk_mul_f32 v[24:25], v[10:11], v[26:27]
	v_ashrrev_i32_e32 v26, 8, v22
	v_add_f32_e32 v24, v24, v25
	v_ashrrev_i32_e32 v25, 4, v22
	v_add_u32_e32 v25, v25, v26
	v_fmac_f32_e32 v24, v7, v28
	v_add_lshl_u32 v25, v22, v25, 2
	v_mul_f32_e32 v24, 0x3e800000, v24
	v_add_u32_e32 v26, 0, v25
	ds_write_b32 v26, v23
	v_cvt_pk_f16_f32 v23, v32, v24
	v_add_u32_e32 v24, s66, v25
	ds_write_b32 v24, v23
	v_add_u32_e32 v23, 0x2000, v22
	v_ashrrev_i32_e32 v24, 4, v23
	v_ashrrev_i32_e32 v23, 8, v23
	v_add_u32_e32 v23, v24, v23
	v_add_lshl_u32 v23, v22, v23, 2
	v_add_u32_e32 v24, 0, v23
	v_add_u32_e32 v23, s66, v23
	ds_write_b32 v23, v97 offset:32768
	v_add_u32_e32 v23, 0x200, v22
	v_max_i32_e32 v96, 1, v23
	ds_write_b32 v24, v97 offset:32768
	v_min_i32_e32 v24, 0x1ffe, v23
	v_lshlrev_b64 v[28:29], 2, v[96:97]
	v_ashrrev_i32_e32 v25, 31, v24
	v_lshl_add_u64 v[30:31], s[58:59], 0, v[28:29]
	v_mov_b32_e32 v27, v113
	v_lshlrev_b64 v[24:25], 2, v[24:25]
	v_mov_b32_e32 v26, v112
	v_lshl_add_u64 v[30:31], s[58:59], 0, v[24:25]
	v_mov_b32_e32 v30, v114
	v_cmp_lt_i32_e32 vcc, 0, v23
	v_cmp_gt_i32_e64 s[40:41], s29, v23
	v_lshl_add_u64 v[20:21], v[20:21], 0, s[46:47]
	s_nop 0
	v_cndmask_b32_e32 v27, 0, v27, vcc
	s_nop 0
	v_pk_mul_f32 v[26:27], v[0:1], v[26:27]
	s_nop 0
	v_add_f32_e32 v26, v26, v27
	s_nop 0
	v_cndmask_b32_e64 v30, 0, v30, s[40:41]
	v_fmac_f32_e32 v26, v4, v30
	v_lshl_add_u64 v[30:31], s[62:63], 0, v[28:29]
	v_mov_b32_e32 v27, v116
	v_mul_f32_e32 v32, 0x3e800000, v26
	v_mov_b32_e32 v26, v115
	v_lshl_add_u64 v[30:31], s[62:63], 0, v[24:25]
	v_mov_b32_e32 v30, v117
	v_lshl_add_u64 v[18:19], v[18:19], 0, s[46:47]
	s_nop 0
	v_cndmask_b32_e32 v27, 0, v27, vcc
	s_nop 0
	v_pk_mul_f32 v[26:27], v[8:9], v[26:27]
	s_nop 0
	v_add_f32_e32 v26, v26, v27
	s_nop 0
	v_cndmask_b32_e64 v30, 0, v30, s[40:41]
	v_fmac_f32_e32 v26, v5, v30
	v_lshl_add_u64 v[30:31], s[18:19], 0, v[28:29]
	v_mov_b32_e32 v27, v119
	v_mul_f32_e32 v33, 0x3e800000, v26
	v_mov_b32_e32 v26, v118
	v_lshl_add_u64 v[30:31], s[18:19], 0, v[24:25]
	v_mov_b32_e32 v30, v120
	v_lshl_add_u64 v[28:29], s[16:17], 0, v[28:29]
	v_lshl_add_u64 v[24:25], s[16:17], 0, v[24:25]
	v_lshl_add_u64 v[16:17], v[16:17], 0, s[46:47]
	v_mov_b32_e32 v24, v123
	s_nop 0
	v_cndmask_b32_e32 v27, 0, v27, vcc
	s_nop 0
	v_pk_mul_f32 v[26:27], v[2:3], v[26:27]
	s_nop 0
	v_add_f32_e32 v26, v26, v27
	v_mov_b32_e32 v27, v122
	s_nop 0
	v_cndmask_b32_e64 v30, 0, v30, s[40:41]
	v_fmac_f32_e32 v26, v6, v30
	v_mul_f32_e32 v30, 0x3e800000, v26
	v_mov_b32_e32 v26, v121
	v_lshl_add_u64 v[14:15], v[14:15], 0, s[46:47]
	s_nop 0
	v_cndmask_b32_e64 v28, 0, v24, s[40:41]
	s_nop 0
	v_cndmask_b32_e32 v27, 0, v27, vcc
	s_nop 0
	v_pk_mul_f32 v[24:25], v[10:11], v[26:27]
	s_nop 0
	v_add_f32_e32 v24, v24, v25
	v_ashrrev_i32_e32 v26, 4, v23
	v_ashrrev_i32_e32 v23, 8, v23
	v_fmac_f32_e32 v24, v7, v28
	v_add_u32_e32 v23, v26, v23
	v_mul_f32_e32 v24, 0x3e800000, v24
	v_add_lshl_u32 v23, v22, v23, 2
	v_add_u32_e32 v26, 0, v23
	v_cvt_pk_f16_f32 v24, v30, v24
	v_add_u32_e32 v23, s66, v23
	ds_write_b32 v23, v24 offset:2048
	v_add_u32_e32 v23, 0x2200, v22
	v_ashrrev_i32_e32 v24, 4, v23
	v_ashrrev_i32_e32 v23, 8, v23
	v_add_u32_e32 v23, v24, v23
	v_add_lshl_u32 v23, v22, v23, 2
	v_cvt_pk_f16_f32 v25, v32, v33
	v_add_u32_e32 v24, 0, v23
	ds_write_b32 v26, v25 offset:2048
	ds_write_b32 v24, v97 offset:34816
	v_add_u32_e32 v24, 0x400, v22
	v_ashrrev_i32_e32 v25, 31, v24
	v_max_i32_e32 v96, 1, v24
	v_min_i32_e32 v26, 0x1ffe, v24
	v_lshlrev_b64 v[28:29], 2, v[24:25]
	v_lshlrev_b64 v[32:33], 2, v[96:97]
	v_add_u32_e32 v23, s66, v23
; DI void hyena_item(const Params& p, int l, int dpr, LAS unsigned char* lds) {
;     ...
;     for (int r = 0; r < 16; ++r) { const int t = tid + NTHR * r;
;         float v[4];
; #pragma unroll
;         for (int c = 0; c < 4; ++c) v[c] = conv3(bint + (size_t)(a + c) * S, t, w[c][0], w[c][1], w[c][2]) * 0.25f;
;         X0[XI(t)] = (hc){(_Float16)v[0], (_Float16)v[1]}; X1[XI(t)] = (hc){(_Float16)v[2], (_Float16)v[3]};
;         X0[XI(t + 8192)] = hzero; X1[XI(t + 8192)] = hzero; }
;     __syncthreads();
	v_ashrrev_i32_e32 v27, 31, v26
	v_lshl_add_u64 v[30:31], s[58:59], 0, v[28:29]
	v_lshl_add_u64 v[34:35], s[58:59], 0, v[32:33]
	ds_write_b32 v23, v97 offset:34816
	v_mov_b32_e32 v30, v124
	v_lshlrev_b64 v[26:27], 2, v[26:27]
	v_mov_b32_e32 v23, v125
	v_lshl_add_u64 v[34:35], s[58:59], 0, v[26:27]
	v_mov_b32_e32 v25, v126
	v_cmp_lt_i32_e32 vcc, 0, v24
	v_cmp_gt_i32_e64 s[40:41], s29, v24
	v_lshl_add_u64 v[34:35], s[62:63], 0, v[32:33]
	s_nop 0
	v_cndmask_b32_e32 v31, 0, v23, vcc
	v_pk_mul_f32 v[30:31], v[0:1], v[30:31]
	s_nop 0
	v_cndmask_b32_e64 v23, 0, v25, s[40:41]
	v_add_f32_e32 v25, v30, v31
	v_fmac_f32_e32 v25, v4, v23
	v_lshl_add_u64 v[30:31], s[62:63], 0, v[28:29]
	v_mul_f32_e32 v23, 0x3e800000, v25
	v_mov_b32_e32 v30, v127
	s_nop 0
	v_mov_b32_e32 v25, v128
	v_lshl_add_u64 v[34:35], s[62:63], 0, v[26:27]
	v_mov_b32_e32 v34, v129
	s_nop 0
	v_cndmask_b32_e32 v31, 0, v25, vcc
	v_pk_mul_f32 v[30:31], v[8:9], v[30:31]
	s_nop 0
	v_cndmask_b32_e64 v25, 0, v34, s[40:41]
	v_add_f32_e32 v30, v30, v31
	v_fmac_f32_e32 v30, v5, v25
	v_mul_f32_e32 v25, 0x3e800000, v30
	v_lshl_add_u64 v[30:31], s[18:19], 0, v[28:29]
	v_lshl_add_u64 v[34:35], s[18:19], 0, v[32:33]
	v_lshl_add_u64 v[28:29], s[16:17], 0, v[28:29]
	v_mov_b32_e32 v30, v130
	v_cvt_pk_f16_f32 v23, v23, v25
	v_mov_b32_e32 v28, v133
	v_ashrrev_i32_e32 v25, 4, v24
	v_mov_b32_e32 v31, v131
	v_lshl_add_u64 v[34:35], s[18:19], 0, v[26:27]
	v_mov_b32_e32 v34, v132
	v_lshl_add_u64 v[26:27], s[16:17], 0, v[26:27]
	v_mov_b32_e32 v26, v135
	v_ashrrev_i32_e32 v24, 8, v24
	v_add_u32_e32 v24, v25, v24
	v_add_lshl_u32 v24, v22, v24, 2
	v_add_u32_e32 v25, 0, v24
	ds_write_b32 v25, v23 offset:4096
	v_add_u32_e32 v24, s66, v24
	s_nop 0
	v_cndmask_b32_e32 v31, 0, v31, vcc
	v_pk_mul_f32 v[30:31], v[2:3], v[30:31]
	s_nop 0
	v_cndmask_b32_e64 v34, 0, v34, s[40:41]
	v_add_f32_e32 v30, v30, v31
	v_fmac_f32_e32 v30, v6, v34
	v_mul_f32_e32 v34, 0x3e800000, v30
	v_lshl_add_u64 v[30:31], s[16:17], 0, v[32:33]
	v_mov_b32_e32 v29, v134
	s_nop 0
	v_cndmask_b32_e64 v30, 0, v26, s[40:41]
	s_nop 0
	v_cndmask_b32_e32 v29, 0, v29, vcc
	v_pk_mul_f32 v[26:27], v[10:11], v[28:29]
	s_nop 0
	v_add_f32_e32 v26, v26, v27
	v_fmac_f32_e32 v26, v7, v30
	v_mul_f32_e32 v26, 0x3e800000, v26
	v_cvt_pk_f16_f32 v23, v34, v26
	ds_write_b32 v24, v23 offset:4096
	v_add_u32_e32 v23, 0x2400, v22
	v_ashrrev_i32_e32 v24, 4, v23
	v_ashrrev_i32_e32 v23, 8, v23
	v_add_u32_e32 v23, v24, v23
	v_add_lshl_u32 v23, v22, v23, 2
	v_add_u32_e32 v24, 0, v23
	ds_write_b32 v24, v97 offset:36864
	v_add_u32_e32 v24, 0x600, v22
	v_ashrrev_i32_e32 v25, 31, v24
	v_max_i32_e32 v96, 1, v24
	v_min_i32_e32 v26, 0x1ffe, v24
	v_lshlrev_b64 v[28:29], 2, v[24:25]
	v_lshlrev_b64 v[32:33], 2, v[96:97]
	v_add_u32_e32 v23, s66, v23
	v_ashrrev_i32_e32 v27, 31, v26
	v_lshl_add_u64 v[30:31], s[58:59], 0, v[28:29]
	v_lshl_add_u64 v[34:35], s[58:59], 0, v[32:33]
	ds_write_b32 v23, v97 offset:36864
	v_mov_b32_e32 v30, v136
	v_lshlrev_b64 v[26:27], 2, v[26:27]
	v_mov_b32_e32 v23, v137
	v_lshl_add_u64 v[34:35], s[58:59], 0, v[26:27]
	v_mov_b32_e32 v25, v138
	v_cmp_lt_i32_e32 vcc, 0, v24
	v_cmp_gt_i32_e64 s[40:41], s29, v24
	v_lshl_add_u64 v[34:35], s[62:63], 0, v[32:33]
	s_nop 0
	v_cndmask_b32_e32 v31, 0, v23, vcc
	v_pk_mul_f32 v[30:31], v[0:1], v[30:31]
	s_nop 0
	v_cndmask_b32_e64 v23, 0, v25, s[40:41]
	v_add_f32_e32 v25, v30, v31
	v_fmac_f32_e32 v25, v4, v23
	v_lshl_add_u64 v[30:31], s[62:63], 0, v[28:29]
	v_mul_f32_e32 v23, 0x3e800000, v25
	v_mov_b32_e32 v30, v139
	s_nop 0
	v_mov_b32_e32 v25, v140
	v_lshl_add_u64 v[34:35], s[62:63], 0, v[26:27]
	v_mov_b32_e32 v34, v141
	s_nop 0
	v_cndmask_b32_e32 v31, 0, v25, vcc
	v_pk_mul_f32 v[30:31], v[8:9], v[30:31]
	s_nop 0
	v_cndmask_b32_e64 v25, 0, v34, s[40:41]
	v_add_f32_e32 v30, v30, v31
	v_fmac_f32_e32 v30, v5, v25
	v_mul_f32_e32 v25, 0x3e800000, v30
	v_lshl_add_u64 v[30:31], s[18:19], 0, v[28:29]
	v_lshl_add_u64 v[34:35], s[18:19], 0, v[32:33]
	v_lshl_add_u64 v[28:29], s[16:17], 0, v[28:29]
	v_mov_b32_e32 v30, v142
	v_cvt_pk_f16_f32 v23, v23, v25
	v_mov_b32_e32 v28, v145
	v_ashrrev_i32_e32 v25, 4, v24
	v_mov_b32_e32 v31, v143
	v_lshl_add_u64 v[34:35], s[18:19], 0, v[26:27]
	v_mov_b32_e32 v34, v144
	v_lshl_add_u64 v[26:27], s[16:17], 0, v[26:27]
	v_mov_b32_e32 v26, v147
	v_ashrrev_i32_e32 v24, 8, v24
	v_add_u32_e32 v24, v25, v24
	v_add_lshl_u32 v24, v22, v24, 2
	v_add_u32_e32 v25, 0, v24
	ds_write_b32 v25, v23 offset:6144
	v_add_u32_e32 v24, s66, v24
	s_nop 0
	v_cndmask_b32_e32 v31, 0, v31, vcc
	v_pk_mul_f32 v[30:31], v[2:3], v[30:31]
	s_nop 0
	v_cndmask_b32_e64 v34, 0, v34, s[40:41]
	v_add_f32_e32 v30, v30, v31
	v_fmac_f32_e32 v30, v6, v34
	v_mul_f32_e32 v34, 0x3e800000, v30
	v_lshl_add_u64 v[30:31], s[16:17], 0, v[32:33]
	v_mov_b32_e32 v29, v146
	s_nop 0
	v_cndmask_b32_e64 v30, 0, v26, s[40:41]
	s_nop 0
	v_cndmask_b32_e32 v29, 0, v29, vcc
	v_pk_mul_f32 v[26:27], v[10:11], v[28:29]
	s_nop 0
	v_add_f32_e32 v26, v26, v27
	v_fmac_f32_e32 v26, v7, v30
	v_mul_f32_e32 v26, 0x3e800000, v26
	v_cvt_pk_f16_f32 v23, v34, v26
	ds_write_b32 v24, v23 offset:6144
	v_add_u32_e32 v23, 0x2600, v22
	v_ashrrev_i32_e32 v24, 4, v23
	v_ashrrev_i32_e32 v23, 8, v23
	v_add_u32_e32 v23, v24, v23
	v_add_lshl_u32 v22, v22, v23, 2
	v_add_u32_e32 v23, 0, v22
	v_add_u32_e32 v22, s66, v22
	ds_write_b32 v23, v97 offset:38912
	ds_write_b32 v22, v97 offset:38912
	s_cbranch_scc0 .LBB0_601
	v_mov_b32_e32 v0, v12
	s_waitcnt lgkmcnt(0)
	s_barrier
	s_nop 0
	v_cmp_gt_i32_e32 vcc, s45, v0
	s_and_saveexec_b64 s[20:21], vcc
	s_movk_i32 s6, 0xc000
	s_movk_i32 s8, 0xdff
	s_mov_b64 s[26:27], 0x10000
	s_cbranch_execz .LBB0_605
	v_lshlrev_b32_e32 v1, 2, v0
	s_mov_b64 s[22:23], 0

; DI void hyena_item(const Params& p, int l, int dpr, LAS unsigned char* lds) {
;     ...
;     for (int r = 0; r < 16; ++r) { const int t = tid + NTHR * r; const hc y0 = X0[XI(t)], y1 = X1[XI(t)];
;         const float yv[4] = {(float)y0.x, (float)y0.y, (float)y1.x, (float)y1.y};
; #pragma unroll
;         for (int c = 0; c < 4; ++c) z2t[(size_t)(a + c) * S + t] = yv[c] * (1.0f / 64.0f) * conv3(bint + (size_t)(2048 + a + c) * S, t, w[c][0], w[c][1], w[c][2]); }
.LBB0_797:
	v_add_u32_e32 v14, s7, v12
	v_mov_b32_e32 v149, 0
	v_mov_b32_e32 v151, 0
	v_mov_b32_e32 v153, 0
	v_mov_b32_e32 v148, v14
	v_max_i32_e32 v150, 1, v148
	v_min_i32_e32 v152, 0x1ffe, v148
	v_lshlrev_b32_e32 v148, 2, v148
	v_lshlrev_b32_e32 v150, 2, v150
	v_lshlrev_b32_e32 v152, 2, v152
	v_lshl_add_u64 v[154:155], s[24:25], 0, v[148:149]
	global_load_dword v100, v[154:155], off
	v_lshl_add_u64 v[154:155], s[24:25], 0, v[150:151]
	global_load_dword v101, v[154:155], off offset:-4
	v_lshl_add_u64 v[154:155], s[24:25], 0, v[152:153]
	global_load_dword v102, v[154:155], off offset:4
	v_lshl_add_u64 v[154:155], s[22:23], 0, v[148:149]
	global_load_dword v103, v[154:155], off
	v_lshl_add_u64 v[154:155], s[22:23], 0, v[150:151]
	global_load_dword v104, v[154:155], off offset:-4
	v_lshl_add_u64 v[154:155], s[22:23], 0, v[152:153]
	global_load_dword v105, v[154:155], off offset:4
	v_lshl_add_u64 v[154:155], s[18:19], 0, v[148:149]
	global_load_dword v106, v[154:155], off
	v_lshl_add_u64 v[154:155], s[18:19], 0, v[150:151]
	global_load_dword v107, v[154:155], off offset:-4
	v_lshl_add_u64 v[154:155], s[18:19], 0, v[152:153]
	global_load_dword v108, v[154:155], off offset:4
	v_lshl_add_u64 v[154:155], s[16:17], 0, v[148:149]
	global_load_dword v109, v[154:155], off
	v_lshl_add_u64 v[154:155], s[16:17], 0, v[150:151]
	global_load_dword v110, v[154:155], off offset:-4
	v_lshl_add_u64 v[154:155], s[16:17], 0, v[152:153]
	global_load_dword v111, v[154:155], off offset:4
	v_add_u32_e32 v148, 0x200, v14
	v_max_i32_e32 v150, 1, v148
	v_min_i32_e32 v152, 0x1ffe, v148
	v_lshlrev_b32_e32 v148, 2, v148
	v_lshlrev_b32_e32 v150, 2, v150
	v_lshlrev_b32_e32 v152, 2, v152
	v_lshl_add_u64 v[154:155], s[24:25], 0, v[148:149]
	global_load_dword v112, v[154:155], off
	v_lshl_add_u64 v[154:155], s[24:25], 0, v[150:151]
	global_load_dword v113, v[154:155], off offset:-4
	v_lshl_add_u64 v[154:155], s[24:25], 0, v[152:153]
	global_load_dword v114, v[154:155], off offset:4
	v_lshl_add_u64 v[154:155], s[22:23], 0, v[148:149]
	global_load_dword v115, v[154:155], off
	v_lshl_add_u64 v[154:155], s[22:23], 0, v[150:151]
	global_load_dword v116, v[154:155], off offset:-4
	v_lshl_add_u64 v[154:155], s[22:23], 0, v[152:153]
	global_load_dword v117, v[154:155], off offset:4
	v_lshl_add_u64 v[154:155], s[18:19], 0, v[148:149]
	global_load_dword v118, v[154:155], off
	v_lshl_add_u64 v[154:155], s[18:19], 0, v[150:151]
	global_load_dword v119, v[154:155], off offset:-4
	v_lshl_add_u64 v[154:155], s[18:19], 0, v[152:153]
	global_load_dword v120, v[154:155], off offset:4
	v_lshl_add_u64 v[154:155], s[16:17], 0, v[148:149]
	global_load_dword v121, v[154:155], off
	v_lshl_add_u64 v[154:155], s[16:17], 0, v[150:151]
	global_load_dword v122, v[154:155], off offset:-4
	v_lshl_add_u64 v[154:155], s[16:17], 0, v[152:153]
	global_load_dword v123, v[154:155], off offset:4
	v_add_u32_e32 v148, 0x400, v14
	v_max_i32_e32 v150, 1, v148
	v_min_i32_e32 v152, 0x1ffe, v148
	v_lshlrev_b32_e32 v148, 2, v148
	v_lshlrev_b32_e32 v150, 2, v150
	v_lshlrev_b32_e32 v152, 2, v152
	v_lshl_add_u64 v[154:155], s[24:25], 0, v[148:149]
	global_load_dword v124, v[154:155], off
	v_lshl_add_u64 v[154:155], s[24:25], 0, v[150:151]
	global_load_dword v125, v[154:155], off offset:-4
	v_lshl_add_u64 v[154:155], s[24:25], 0, v[152:153]
	global_load_dword v126, v[154:155], off offset:4
	v_lshl_add_u64 v[154:155], s[22:23], 0, v[148:149]
	global_load_dword v127, v[154:155], off
	v_lshl_add_u64 v[154:155], s[22:23], 0, v[150:151]
	global_load_dword v128, v[154:155], off offset:-4
	v_lshl_add_u64 v[154:155], s[22:23], 0, v[152:153]
	global_load_dword v129, v[154:155], off offset:4
	v_lshl_add_u64 v[154:155], s[18:19], 0, v[148:149]
	global_load_dword v130, v[154:155], off
	v_lshl_add_u64 v[154:155], s[18:19], 0, v[150:151]
	global_load_dword v131, v[154:155], off offset:-4
	v_lshl_add_u64 v[154:155], s[18:19], 0, v[152:153]
	global_load_dword v132, v[154:155], off offset:4
	v_lshl_add_u64 v[154:155], s[16:17], 0, v[148:149]
	global_load_dword v133, v[154:155], off
	v_lshl_add_u64 v[154:155], s[16:17], 0, v[150:151]
	global_load_dword v134, v[154:155], off offset:-4
	v_lshl_add_u64 v[154:155], s[16:17], 0, v[152:153]
	global_load_dword v135, v[154:155], off offset:4
	v_add_u32_e32 v148, 0x600, v14
	v_max_i32_e32 v150, 1, v148
	v_min_i32_e32 v152, 0x1ffe, v148
	v_lshlrev_b32_e32 v148, 2, v148
	v_lshlrev_b32_e32 v150, 2, v150
	v_lshlrev_b32_e32 v152, 2, v152
	v_lshl_add_u64 v[154:155], s[24:25], 0, v[148:149]
	global_load_dword v136, v[154:155], off
	v_lshl_add_u64 v[154:155], s[24:25], 0, v[150:151]
	global_load_dword v137, v[154:155], off offset:-4
	v_lshl_add_u64 v[154:155], s[24:25], 0, v[152:153]
	global_load_dword v138, v[154:155], off offset:4
	v_lshl_add_u64 v[154:155], s[22:23], 0, v[148:149]
	global_load_dword v139, v[154:155], off
	v_lshl_add_u64 v[154:155], s[22:23], 0, v[150:151]
	global_load_dword v140, v[154:155], off offset:-4
	v_lshl_add_u64 v[154:155], s[22:23], 0, v[152:153]
	global_load_dword v141, v[154:155], off offset:4
	v_lshl_add_u64 v[154:155], s[18:19], 0, v[148:149]
	global_load_dword v142, v[154:155], off
	v_lshl_add_u64 v[154:155], s[18:19], 0, v[150:151]
	global_load_dword v143, v[154:155], off offset:-4
	v_lshl_add_u64 v[154:155], s[18:19], 0, v[152:153]
	global_load_dword v144, v[154:155], off offset:4
	v_lshl_add_u64 v[154:155], s[16:17], 0, v[148:149]
	global_load_dword v145, v[154:155], off
	v_lshl_add_u64 v[154:155], s[16:17], 0, v[150:151]
	global_load_dword v146, v[154:155], off offset:-4
	v_lshl_add_u64 v[154:155], s[16:17], 0, v[152:153]
	global_load_dword v147, v[154:155], off offset:4
	s_waitcnt vmcnt(0)
; DI void hyena_item(const Params& p, int l, int dpr, LAS unsigned char* lds) {
;     ...
;     for (int r = 0; r < 16; ++r) { const int t = tid + NTHR * r; const hc y0 = X0[XI(t)], y1 = X1[XI(t)];
;         const float yv[4] = {(float)y0.x, (float)y0.y, (float)y1.x, (float)y1.y};
; #pragma unroll
;         for (int c = 0; c < 4; ++c) z2t[(size_t)(a + c) * S + t] = yv[c] * (1.0f / 64.0f) * conv3(bint + (size_t)(2048 + a + c) * S, t, w[c][0], w[c][1], w[c][2]); }
	v_ashrrev_i32_e32 v13, 4, v14
	v_ashrrev_i32_e32 v15, 8, v14
	v_add_u32_e32 v13, v13, v15
	v_add_lshl_u32 v13, v14, v13, 2
	v_add_u32_e32 v15, 0, v13
	ds_read_b32 v15, v15
	v_add_u32_e32 v13, s66, v13
	ds_read_b32 v13, v13
	v_max_i32_e32 v96, 1, v14
	v_min_i32_e32 v18, 0x1ffe, v14
	s_waitcnt lgkmcnt(1)
	v_cvt_f32_f16_e32 v20, v15
	v_cvt_f32_f16_sdwa v26, v15 dst_sel:DWORD dst_unused:UNUSED_PAD src0_sel:WORD_1
	v_ashrrev_i32_e32 v15, 31, v14
	v_lshlrev_b64 v[22:23], 2, v[14:15]
	v_mul_f32_e32 v15, 0x3c800000, v20
	v_lshl_add_u64 v[20:21], s[24:25], 0, v[22:23]
	v_mov_b32_e32 v28, v100
	v_lshlrev_b64 v[20:21], 2, v[96:97]
	v_ashrrev_i32_e32 v19, 31, v18
	v_lshl_add_u64 v[24:25], s[24:25], 0, v[20:21]
	v_mov_b32_e32 v29, v101
	v_lshlrev_b64 v[18:19], 2, v[18:19]
	v_lshl_add_u64 v[24:25], s[24:25], 0, v[18:19]
	v_mov_b32_e32 v24, v102
	v_cmp_lt_i32_e32 vcc, 0, v14
	v_cmp_gt_i32_e64 s[40:41], s29, v14
	v_lshl_add_u64 v[16:17], s[20:21], 0, v[22:23]
	s_waitcnt lgkmcnt(0)
	v_cvt_f32_f16_e32 v27, v13
	v_cvt_f32_f16_sdwa v13, v13 dst_sel:DWORD dst_unused:UNUSED_PAD src0_sel:WORD_1
	s_addk_i32 s7, 0x800
	s_cmpk_lg_i32 s7, 0x2000
	v_mul_f32_e32 v13, 0x3c800000, v13
	s_nop 0
	v_cndmask_b32_e32 v25, 0, v29, vcc
	v_mul_f32_e32 v25, v0, v25
	v_fmac_f32_e32 v25, v4, v28
	s_nop 0
	v_cndmask_b32_e64 v24, 0, v24, s[40:41]
	v_fmac_f32_e32 v25, v8, v24
	v_mul_f32_e32 v15, v15, v25
	v_lshl_add_u64 v[24:25], v[16:17], 0, s[50:51]
	global_store_dword v[24:25], v15, off
	v_lshl_add_u64 v[24:25], s[22:23], 0, v[22:23]
	v_mul_f32_e32 v15, 0x3c800000, v26
	v_mov_b32_e32 v26, v103
	v_lshl_add_u64 v[24:25], s[22:23], 0, v[20:21]
	v_mov_b32_e32 v28, v104
	v_lshl_add_u64 v[24:25], s[22:23], 0, v[18:19]
	v_mov_b32_e32 v24, v105
	s_nop 0
	v_cndmask_b32_e32 v25, 0, v28, vcc
	v_mul_f32_e32 v25, v1, v25
	s_nop 0
	v_cndmask_b32_e64 v24, 0, v24, s[40:41]
	v_fmac_f32_e32 v25, v5, v26
	v_fmac_f32_e32 v25, v9, v24
	v_mul_f32_e32 v15, v15, v25
	v_lshl_add_u64 v[24:25], v[16:17], 0, s[52:53]
	global_store_dword v[24:25], v15, off
	v_lshl_add_u64 v[24:25], s[18:19], 0, v[22:23]
	v_mov_b32_e32 v26, v106
	v_lshl_add_u64 v[24:25], s[18:19], 0, v[20:21]
	v_mul_f32_e32 v15, 0x3c800000, v27
	v_mov_b32_e32 v27, v107
	v_lshl_add_u64 v[24:25], s[18:19], 0, v[18:19]
	v_mov_b32_e32 v24, v108
	v_lshl_add_u64 v[22:23], s[16:17], 0, v[22:23]
	v_lshl_add_u64 v[20:21], s[16:17], 0, v[20:21]
	v_lshl_add_u64 v[18:19], s[16:17], 0, v[18:19]
	s_nop 0
	v_cndmask_b32_e32 v25, 0, v27, vcc
	v_mul_f32_e32 v25, v2, v25
	s_nop 0
	v_cndmask_b32_e64 v24, 0, v24, s[40:41]
	v_fmac_f32_e32 v25, v6, v26
	v_fmac_f32_e32 v25, v10, v24
	v_mul_f32_e32 v15, v15, v25
	v_lshl_add_u64 v[24:25], v[16:17], 0, s[54:55]
	global_store_dword v[24:25], v15, off
	v_mov_b32_e32 v15, v109
	v_lshl_add_u64 v[16:17], v[16:17], 0, s[56:57]
	v_mov_b32_e32 v20, v110
	s_nop 0
	v_mov_b32_e32 v18, v111
	s_nop 0
	v_cndmask_b32_e32 v19, 0, v20, vcc
	v_mul_f32_e32 v19, v3, v19
	s_nop 0
	v_cndmask_b32_e64 v18, 0, v18, s[40:41]
	v_fmac_f32_e32 v19, v7, v15
	v_fmac_f32_e32 v19, v11, v18
	v_mul_f32_e32 v13, v13, v19
	global_store_dword v[16:17], v13, off
	v_add_u32_e32 v16, 0x200, v14
	v_ashrrev_i32_e32 v13, 4, v16
	v_ashrrev_i32_e32 v15, 8, v16
	v_add_u32_e32 v13, v13, v15
	v_add_lshl_u32 v13, v14, v13, 2
	v_add_u32_e32 v15, 0, v13
	ds_read_b32 v15, v15 offset:2048
	v_add_u32_e32 v13, s66, v13
	ds_read_b32 v13, v13 offset:2048
	v_ashrrev_i32_e32 v17, 31, v16
	v_cmp_lt_i32_e32 vcc, 0, v16
	s_waitcnt lgkmcnt(1)
	v_cvt_f32_f16_e32 v18, v15
	v_max_i32_e32 v96, 1, v16
	v_cmp_gt_i32_e64 s[40:41], s29, v16
	v_min_i32_e32 v20, 0x1ffe, v16
	v_lshlrev_b64 v[16:17], 2, v[16:17]
	v_mul_f32_e32 v25, 0x3c800000, v18
	v_lshl_add_u64 v[18:19], s[24:25], 0, v[16:17]
	v_mov_b32_e32 v26, v112
	v_lshlrev_b64 v[18:19], 2, v[96:97]
	v_ashrrev_i32_e32 v21, 31, v20
	v_lshl_add_u64 v[22:23], s[24:25], 0, v[18:19]
	v_mov_b32_e32 v27, v113
	v_lshlrev_b64 v[20:21], 2, v[20:21]
	v_lshl_add_u64 v[22:23], s[24:25], 0, v[20:21]
	v_mov_b32_e32 v22, v114
	v_cvt_f32_f16_sdwa v15, v15 dst_sel:DWORD dst_unused:UNUSED_PAD src0_sel:WORD_1
	s_waitcnt lgkmcnt(0)
	v_cvt_f32_f16_e32 v24, v13
	v_cvt_f32_f16_sdwa v13, v13 dst_sel:DWORD dst_unused:UNUSED_PAD src0_sel:WORD_1
	v_mul_f32_e32 v15, 0x3c800000, v15
	v_mul_f32_e32 v13, 0x3c800000, v13
	s_nop 0
	v_cndmask_b32_e32 v23, 0, v27, vcc
	v_mul_f32_e32 v23, v0, v23
	v_fmac_f32_e32 v23, v4, v26
	s_nop 0
	v_cndmask_b32_e64 v22, 0, v22, s[40:41]
	v_fmac_f32_e32 v23, v8, v22
	v_mul_f32_e32 v25, v25, v23
	v_lshl_add_u64 v[22:23], s[26:27], 0, v[16:17]
	global_store_dword v[22:23], v25, off
	v_lshl_add_u64 v[22:23], s[22:23], 0, v[16:17]
	v_mov_b32_e32 v25, v115
	v_lshl_add_u64 v[22:23], s[22:23], 0, v[18:19]
	v_mov_b32_e32 v26, v116
	v_lshl_add_u64 v[22:23], s[22:23], 0, v[20:21]
	v_mov_b32_e32 v22, v117
	s_nop 0
	v_cndmask_b32_e32 v23, 0, v26, vcc
	v_mul_f32_e32 v23, v1, v23
	s_nop 0
	v_cndmask_b32_e64 v22, 0, v22, s[40:41]
	v_fmac_f32_e32 v23, v5, v25
	v_fmac_f32_e32 v23, v9, v22
	v_mul_f32_e32 v15, v15, v23
	v_lshl_add_u64 v[22:23], s[42:43], 0, v[16:17]
	global_store_dword v[22:23], v15, off
	v_lshl_add_u64 v[22:23], s[18:19], 0, v[16:17]
	v_mul_f32_e32 v15, 0x3c800000, v24
	v_mov_b32_e32 v24, v118
	v_lshl_add_u64 v[22:23], s[18:19], 0, v[18:19]
	v_mov_b32_e32 v25, v119
	v_lshl_add_u64 v[22:23], s[18:19], 0, v[20:21]
	v_mov_b32_e32 v22, v120
	v_lshl_add_u64 v[18:19], s[16:17], 0, v[18:19]
	s_nop 0
	v_cndmask_b32_e32 v23, 0, v25, vcc
	v_mul_f32_e32 v23, v2, v23
	s_nop 0
	v_cndmask_b32_e64 v22, 0, v22, s[40:41]
	v_fmac_f32_e32 v23, v6, v24
	v_fmac_f32_e32 v23, v10, v22
	v_mul_f32_e32 v15, v15, v23
	v_lshl_add_u64 v[22:23], s[58:59], 0, v[16:17]
	global_store_dword v[22:23], v15, off
	v_lshl_add_u64 v[22:23], s[16:17], 0, v[16:17]
	v_mov_b32_e32 v15, v121
	v_lshl_add_u64 v[16:17], s[60:61], 0, v[16:17]
	v_mov_b32_e32 v22, v122
	v_lshl_add_u64 v[18:19], s[16:17], 0, v[20:21]
	v_mov_b32_e32 v18, v123
	s_nop 0
	v_cndmask_b32_e32 v19, 0, v22, vcc
	v_mul_f32_e32 v19, v3, v19
	s_nop 0
	v_cndmask_b32_e64 v18, 0, v18, s[40:41]
	v_fmac_f32_e32 v19, v7, v15
	v_fmac_f32_e32 v19, v11, v18
	v_mul_f32_e32 v13, v13, v19
	global_store_dword v[16:17], v13, off
	v_add_u32_e32 v16, 0x400, v14
	v_ashrrev_i32_e32 v13, 4, v16
	v_ashrrev_i32_e32 v15, 8, v16
	v_add_u32_e32 v13, v13, v15
	v_add_lshl_u32 v13, v14, v13, 2
	v_add_u32_e32 v15, 0, v13
	ds_read_b32 v15, v15 offset:4096
	v_add_u32_e32 v13, s66, v13
	ds_read_b32 v13, v13 offset:4096
	v_ashrrev_i32_e32 v17, 31, v16
	v_lshlrev_b64 v[22:23], 2, v[16:17]
	s_waitcnt lgkmcnt(1)
; DI void hyena_item(const Params& p, int l, int dpr, LAS unsigned char* lds) {
;     ...
;     for (int r = 0; r < 16; ++r) { const int t = tid + NTHR * r; const hc y0 = X0[XI(t)], y1 = X1[XI(t)];
;         const float yv[4] = {(float)y0.x, (float)y0.y, (float)y1.x, (float)y1.y};
; #pragma unroll
;         for (int c = 0; c < 4; ++c) z2t[(size_t)(a + c) * S + t] = yv[c] * (1.0f / 64.0f) * conv3(bint + (size_t)(2048 + a + c) * S, t, w[c][0], w[c][1], w[c][2]); }
;     __syncthreads();
	v_cvt_f32_f16_e32 v18, v15
	v_max_i32_e32 v96, 1, v16
	v_min_i32_e32 v20, 0x1ffe, v16
	v_ashrrev_i32_e32 v21, 31, v20
	v_mul_f32_e32 v27, 0x3c800000, v18
	v_lshl_add_u64 v[18:19], s[24:25], 0, v[22:23]
	v_mov_b32_e32 v28, v124
	v_lshlrev_b64 v[18:19], 2, v[96:97]
	v_lshl_add_u64 v[24:25], s[24:25], 0, v[18:19]
	v_mov_b32_e32 v29, v125
	v_lshlrev_b64 v[20:21], 2, v[20:21]
	v_lshl_add_u64 v[24:25], s[24:25], 0, v[20:21]
	v_mov_b32_e32 v24, v126
	v_cmp_lt_i32_e32 vcc, 0, v16
	v_cmp_gt_i32_e64 s[40:41], s29, v16
	v_lshl_add_u64 v[16:17], s[20:21], 0, v[22:23]
	v_cvt_f32_f16_sdwa v15, v15 dst_sel:DWORD dst_unused:UNUSED_PAD src0_sel:WORD_1
	s_waitcnt lgkmcnt(0)
	v_cvt_f32_f16_e32 v26, v13
	v_cvt_f32_f16_sdwa v13, v13 dst_sel:DWORD dst_unused:UNUSED_PAD src0_sel:WORD_1
	v_mul_f32_e32 v15, 0x3c800000, v15
	v_mul_f32_e32 v13, 0x3c800000, v13
	s_nop 0
	v_cndmask_b32_e32 v25, 0, v29, vcc
	v_mul_f32_e32 v25, v0, v25
	v_fmac_f32_e32 v25, v4, v28
	s_nop 0
	v_cndmask_b32_e64 v24, 0, v24, s[40:41]
	v_fmac_f32_e32 v25, v8, v24
	v_mul_f32_e32 v27, v27, v25
	v_lshl_add_u64 v[24:25], v[16:17], 0, s[50:51]
	global_store_dword v[24:25], v27, off
	v_lshl_add_u64 v[24:25], s[22:23], 0, v[22:23]
	v_mov_b32_e32 v27, v127
	v_lshl_add_u64 v[24:25], s[22:23], 0, v[18:19]
	v_mov_b32_e32 v28, v128
	v_lshl_add_u64 v[24:25], s[22:23], 0, v[20:21]
	v_mov_b32_e32 v24, v129
	s_nop 0
	v_cndmask_b32_e32 v25, 0, v28, vcc
	v_mul_f32_e32 v25, v1, v25
	s_nop 0
	v_cndmask_b32_e64 v24, 0, v24, s[40:41]
	v_fmac_f32_e32 v25, v5, v27
	v_fmac_f32_e32 v25, v9, v24
	v_mul_f32_e32 v15, v15, v25
	v_lshl_add_u64 v[24:25], v[16:17], 0, s[52:53]
	global_store_dword v[24:25], v15, off
	v_lshl_add_u64 v[24:25], s[18:19], 0, v[22:23]
	v_mul_f32_e32 v15, 0x3c800000, v26
	v_mov_b32_e32 v26, v130
	v_lshl_add_u64 v[24:25], s[18:19], 0, v[18:19]
	v_mov_b32_e32 v27, v131
	v_lshl_add_u64 v[24:25], s[18:19], 0, v[20:21]
	v_mov_b32_e32 v24, v132
	v_lshl_add_u64 v[22:23], s[16:17], 0, v[22:23]
	v_lshl_add_u64 v[18:19], s[16:17], 0, v[18:19]
	s_nop 0
	v_cndmask_b32_e32 v25, 0, v27, vcc
	v_mul_f32_e32 v25, v2, v25
	s_nop 0
	v_cndmask_b32_e64 v24, 0, v24, s[40:41]
	v_fmac_f32_e32 v25, v6, v26
	v_fmac_f32_e32 v25, v10, v24
	v_mul_f32_e32 v15, v15, v25
	v_lshl_add_u64 v[24:25], v[16:17], 0, s[54:55]
	global_store_dword v[24:25], v15, off
	v_mov_b32_e32 v15, v133
	v_lshl_add_u64 v[16:17], v[16:17], 0, s[56:57]
	v_mov_b32_e32 v22, v134
	v_lshl_add_u64 v[18:19], s[16:17], 0, v[20:21]
	v_mov_b32_e32 v18, v135
	s_nop 0
	v_cndmask_b32_e32 v19, 0, v22, vcc
	v_mul_f32_e32 v19, v3, v19
	s_nop 0
	v_cndmask_b32_e64 v18, 0, v18, s[40:41]
	v_fmac_f32_e32 v19, v7, v15
	v_fmac_f32_e32 v19, v11, v18
	v_mul_f32_e32 v13, v13, v19
	global_store_dword v[16:17], v13, off
	v_add_u32_e32 v16, 0x600, v14
	v_ashrrev_i32_e32 v13, 4, v16
	v_ashrrev_i32_e32 v15, 8, v16
	v_add_u32_e32 v13, v13, v15
	v_add_lshl_u32 v13, v14, v13, 2
	v_add_u32_e32 v14, 0, v13
	ds_read_b32 v14, v14 offset:6144
	v_add_u32_e32 v13, s66, v13
	ds_read_b32 v13, v13 offset:6144
	v_ashrrev_i32_e32 v17, 31, v16
	v_max_i32_e32 v96, 1, v16
	s_waitcnt lgkmcnt(1)
	v_cvt_f32_f16_e32 v20, v14
	v_lshlrev_b64 v[18:19], 2, v[16:17]
	v_cmp_lt_i32_e32 vcc, 0, v16
	v_cmp_gt_i32_e64 s[40:41], s29, v16
	v_min_i32_e32 v22, 0x1ffe, v16
	v_mul_f32_e32 v26, 0x3c800000, v20
	v_lshl_add_u64 v[16:17], s[24:25], 0, v[18:19]
	v_lshlrev_b64 v[20:21], 2, v[96:97]
	v_ashrrev_i32_e32 v23, 31, v22
	v_mov_b32_e32 v27, v136
	v_lshl_add_u64 v[16:17], s[24:25], 0, v[20:21]
	v_mov_b32_e32 v28, v137
	v_lshlrev_b64 v[16:17], 2, v[22:23]
	v_lshl_add_u64 v[22:23], s[24:25], 0, v[16:17]
	v_mov_b32_e32 v22, v138
	v_cvt_f32_f16_sdwa v24, v14 dst_sel:DWORD dst_unused:UNUSED_PAD src0_sel:WORD_1
	v_lshl_add_u64 v[14:15], s[20:21], 0, v[18:19]
	s_waitcnt lgkmcnt(0)
	v_cvt_f32_f16_e32 v25, v13
	v_cvt_f32_f16_sdwa v13, v13 dst_sel:DWORD dst_unused:UNUSED_PAD src0_sel:WORD_1
	v_mul_f32_e32 v24, 0x3c800000, v24
	v_mul_f32_e32 v13, 0x3c800000, v13
	s_nop 0
	v_cndmask_b32_e32 v23, 0, v28, vcc
	v_mul_f32_e32 v23, v0, v23
	v_fmac_f32_e32 v23, v4, v27
	s_nop 0
	v_cndmask_b32_e64 v22, 0, v22, s[40:41]
	v_fmac_f32_e32 v23, v8, v22
	v_mul_f32_e32 v26, v26, v23
	v_lshl_add_u64 v[22:23], v[14:15], 0, s[50:51]
	global_store_dword v[22:23], v26, off
	v_lshl_add_u64 v[22:23], s[22:23], 0, v[18:19]
	v_mov_b32_e32 v26, v139
	v_lshl_add_u64 v[22:23], s[22:23], 0, v[20:21]
	v_mov_b32_e32 v27, v140
	v_lshl_add_u64 v[22:23], s[22:23], 0, v[16:17]
	v_mov_b32_e32 v22, v141
	s_nop 0
	v_cndmask_b32_e32 v23, 0, v27, vcc
	v_mul_f32_e32 v23, v1, v23
	s_nop 0
	v_cndmask_b32_e64 v22, 0, v22, s[40:41]
	v_fmac_f32_e32 v23, v5, v26
	v_fmac_f32_e32 v23, v9, v22
	v_mul_f32_e32 v24, v24, v23
	v_lshl_add_u64 v[22:23], v[14:15], 0, s[52:53]
	global_store_dword v[22:23], v24, off
	v_lshl_add_u64 v[22:23], s[18:19], 0, v[18:19]
	v_mul_f32_e32 v24, 0x3c800000, v25
	v_mov_b32_e32 v25, v142
	v_lshl_add_u64 v[22:23], s[18:19], 0, v[20:21]
	v_mov_b32_e32 v26, v143
	v_lshl_add_u64 v[22:23], s[18:19], 0, v[16:17]
	v_mov_b32_e32 v22, v144
	v_lshl_add_u64 v[18:19], s[16:17], 0, v[18:19]
	v_lshl_add_u64 v[16:17], s[16:17], 0, v[16:17]
	s_nop 0
	v_cndmask_b32_e32 v23, 0, v26, vcc
	v_mul_f32_e32 v23, v2, v23
	s_nop 0
	v_cndmask_b32_e64 v22, 0, v22, s[40:41]
	v_fmac_f32_e32 v23, v6, v25
	v_fmac_f32_e32 v23, v10, v22
	v_mul_f32_e32 v24, v24, v23
	v_lshl_add_u64 v[22:23], v[14:15], 0, s[54:55]
	global_store_dword v[22:23], v24, off
	v_mov_b32_e32 v22, v145
	v_lshl_add_u64 v[18:19], s[16:17], 0, v[20:21]
	v_mov_b32_e32 v18, v146
	v_lshl_add_u64 v[14:15], v[14:15], 0, s[56:57]
	v_mov_b32_e32 v16, v147
	s_nop 0
	v_cndmask_b32_e32 v17, 0, v18, vcc
	v_mul_f32_e32 v17, v3, v17
	s_nop 0
	v_cndmask_b32_e64 v16, 0, v16, s[40:41]
	v_fmac_f32_e32 v17, v7, v22
	v_fmac_f32_e32 v17, v11, v16
	v_mul_f32_e32 v13, v13, v17
	global_store_dword v[14:15], v13, off
	s_cbranch_scc1 .LBB0_797
	v_readlane_b32 s62, v255, 31
	v_readlane_b32 s54, v255, 58
	v_readlane_b32 s63, v255, 32
	v_readlane_b32 s52, v255, 48
	v_readlane_b32 s55, v255, 59
	v_readlane_b32 s61, v255, 33
	s_movk_i32 s63, 0x2000
	s_mov_b32 s26, 0x800000
	s_mov_b32 s60, 0x78a5c000
	s_mov_b32 s27, 0x9000000
	s_mov_b32 s51, 0x409b43d5
	v_readlane_b32 s53, v255, 49
	v_readlane_b32 s50, v255, 52
	v_readlane_b32 s56, v255, 56
	v_readlane_b32 s58, v255, 54
	s_mov_b32 s55, s2
	s_barrier
	v_readlane_b32 s57, v255, 57
	v_readlane_b32 s59, v255, 55
